# adds P4 merge: 15 sb_out_norm quads requested with the first one, stores back to back (on top of P10 tail + P5 epilogue ring)
# speedup vs baseline: 1.0076x; 1.0056x over previous
; __device__ __forceinline__ unsigned cvt2bf(float lo, float hi) { const f32x2 v = {lo, hi}; return __builtin_bit_cast(unsigned, __builtin_convertvector(v, bf16x2_t)); }
; __device__ __forceinline__ void sb_attn_merge(Frame& F, int u) {
;     ...
;     const float* P0 = WSP(float, WS_APART) + ((size_t)((u * 2 + 0) * 8 + F.wave)) * APART_WAVE + lane;
;     const float* P1 = P0 + 8 * APART_WAVE;
;     const float R0 = P0[32 * 64];
;     f32x16 oacc[4];
; #pragma unroll
;     for (int d = 0; d < 4; ++d)
; #pragma unroll
;         for (int i = 0; i < 16; i += 2) { const unsigned w0 = ((const unsigned*)P0)[(8 * d + (i >> 1)) * 64], w1 = ((const unsigned*)P1)[(8 * d + (i >> 1)) * 64];
;             oacc[d][i] = bf_lo(w0) + R0 * bf_lo(w1); oacc[d][i + 1] = bf_hi(w0) + R0 * bf_hi(w1); }
;     float ss = 0.f;
; #pragma unroll
;     for (int d = 0; d < 4; ++d)
; #pragma unroll
;         for (int i = 0; i < 16; ++i) ss += oacc[d][i] * oacc[d][i];
;     ss += __shfl_xor(ss, 32);
;     const float rs = rsqrtf(ss * (1.f / HD) + EPS);
;     const float* nw = kin(13);
;     bf16* op = MIX + ((size_t)b * T + q0w + r32) * D + h * HD + 4 * hh;
; #pragma unroll
;     for (int d = 0; d < 4; ++d)
; #pragma unroll
;         for (int g = 0; g < 4; ++g) { const int dd = 32 * d + 8 * g + 4 * hh; const f32x4 w4 = *(const f32x4*)(nw + dd);
;             v2u w; w.x = cvt2bf(oacc[d][4 * g] * rs * w4.x, oacc[d][4 * g + 1] * rs * w4.y); w.y = cvt2bf(oacc[d][4 * g + 2] * rs * w4.z, oacc[d][4 * g + 3] * rs * w4.w);
;             *(v2u*)(op + 32 * d + 8 * g) = w; }
.LBB0_1517:
	s_add_i32 s2, s94, s16
	v_mad_i64_i32 v[2:3], s[6:7], s2, v19, v[8:9]
	v_add_co_u32_e64 v10, s[6:7], s18, v2
	v_add_co_u32_e32 v4, vcc, 0x2000, v2
	s_nop 0
	v_addc_co_u32_e64 v11, s[6:7], 0, v3, s[6:7]
	v_add_co_u32_e64 v12, s[6:7], s20, v2
	global_load_dword v16, v[2:3], off
	global_load_dword v17, v[2:3], off offset:256
	global_load_dword v20, v[2:3], off offset:512
	global_load_dword v21, v[2:3], off offset:768
	global_load_dword v22, v[2:3], off offset:1024
	global_load_dword v23, v[2:3], off offset:1280
	global_load_dword v24, v[2:3], off offset:1536
	global_load_dword v25, v[2:3], off offset:1792
	v_addc_co_u32_e64 v13, s[6:7], 0, v3, s[6:7]
	global_load_dword v26, v[2:3], off offset:2048
	global_load_dword v27, v[2:3], off offset:2304
	global_load_dword v28, v[2:3], off offset:2560
	global_load_dword v29, v[2:3], off offset:2816
	global_load_dword v30, v[2:3], off offset:3072
	global_load_dword v31, v[2:3], off offset:3328
	global_load_dword v32, v[2:3], off offset:3584
	global_load_dword v33, v[2:3], off offset:3840
	v_add_co_u32_e64 v14, s[6:7], s19, v2
	v_addc_co_u32_e32 v5, vcc, 0, v3, vcc
	s_nop 0
	v_addc_co_u32_e64 v15, s[6:7], 0, v3, s[6:7]
	v_add_co_u32_e32 v2, vcc, 0x10000, v2
	global_load_dword v34, v[14:15], off
	global_load_dword v35, v[14:15], off offset:256
	global_load_dword v37, v[14:15], off offset:512
	global_load_dword v39, v[14:15], off offset:768
	global_load_dword v42, v[14:15], off offset:1024
	global_load_dword v43, v[14:15], off offset:1280
	global_load_dword v44, v[14:15], off offset:1536
	global_load_dword v45, v[14:15], off offset:1792
	global_load_dword v36, v[10:11], off offset:2048
	global_load_dword v38, v[10:11], off offset:2304
	global_load_dword v40, v[10:11], off offset:2560
	global_load_dword v41, v[10:11], off offset:2816
	global_load_dword v52, v[10:11], off offset:3072
	global_load_dword v53, v[10:11], off offset:3328
	global_load_dword v91, v[10:11], off offset:3584
	global_load_dword v95, v[10:11], off offset:3840
	global_load_dword v80, v[12:13], off offset:-4096
	global_load_dword v99, v[12:13], off
	global_load_dword v103, v[12:13], off offset:256
	global_load_dword v107, v[12:13], off offset:512
	global_load_dword v111, v[12:13], off offset:768
	global_load_dword v115, v[12:13], off offset:1024
	global_load_dword v116, v[12:13], off offset:1280
	global_load_dword v117, v[12:13], off offset:1536
	global_load_dword v97, v[14:15], off offset:2048
	global_load_dword v101, v[14:15], off offset:2304
	global_load_dword v105, v[14:15], off offset:2560
	global_load_dword v109, v[14:15], off offset:2816
	global_load_dword v113, v[14:15], off offset:3072
	global_load_dword v118, v[14:15], off offset:3328
	global_load_dword v119, v[14:15], off offset:3584
	global_load_dword v120, v[14:15], off offset:3840
	global_load_dword v121, v[12:13], off offset:1792
	v_addc_co_u32_e32 v3, vcc, 0, v3, vcc
	global_load_dword v18, v[4:5], off
	global_load_dword v122, v[2:3], off offset:2048
	global_load_dword v123, v[2:3], off offset:2304
	global_load_dword v124, v[2:3], off offset:2560
	global_load_dword v125, v[2:3], off offset:2816
	global_load_dword v126, v[2:3], off offset:3072
	global_load_dword v127, v[2:3], off offset:3328
	global_load_dword v128, v[2:3], off offset:3584
	global_load_dword v129, v[2:3], off offset:3840
	global_load_dword v130, v[10:11], off offset:256
	global_load_dword v131, v[10:11], off offset:512
	global_load_dword v132, v[10:11], off offset:768
	global_load_dword v133, v[10:11], off offset:1024
	global_load_dword v134, v[10:11], off offset:1280
	global_load_dword v135, v[10:11], off offset:1536
	global_load_dword v136, v[10:11], off offset:1792
	s_and_b32 s12, s16, 0xffffff00
	s_add_i32 s12, s12, s3
	s_and_b32 s28, s14, 0x1000
	s_ashr_i32 s2, s12, 31
	s_add_u32 s6, s12, s28
	s_movk_i32 s23, 0x68
	s_addc_u32 s2, s2, 0
	v_or_b32_e32 v12, s6, v182
	s_and_b32 s6, s4, 0x380
	s_lshl_b32 s12, s6, 1
	s_load_dwordx2 s[6:7], s[0:1], s23 offset:0x0
	v_mov_b32_e32 v13, s2
	v_lshlrev_b64 v[2:3], 12, v[12:13]
	v_lshl_add_u64 v[2:3], s[10:11], 0, v[2:3]
	v_lshl_add_u64 v[2:3], v[2:3], 0, s[12:13]
	v_lshl_add_u64 v[10:11], v[2:3], 0, v[6:7]
	s_waitcnt lgkmcnt(0)
	global_load_dwordx4 v[2:5], v78, s[6:7]
	global_load_dwordx4 v[184:187], v78, s[6:7] offset:32
	global_load_dwordx4 v[188:191], v78, s[6:7] offset:64
	global_load_dwordx4 v[192:195], v78, s[6:7] offset:96
	global_load_dwordx4 v[200:203], v78, s[6:7] offset:128
	global_load_dwordx4 v[204:207], v78, s[6:7] offset:160
	global_load_dwordx4 v[208:211], v78, s[6:7] offset:192
	global_load_dwordx4 v[212:215], v78, s[6:7] offset:224
	global_load_dwordx4 v[218:221], v78, s[6:7] offset:256
	global_load_dwordx4 v[222:225], v78, s[6:7] offset:288
	global_load_dwordx4 v[226:229], v78, s[6:7] offset:320
	global_load_dwordx4 v[230:233], v78, s[6:7] offset:352
	global_load_dwordx4 v[234:237], v78, s[6:7] offset:384
	global_load_dwordx4 v[238:241], v78, s[6:7] offset:416
	global_load_dwordx4 v[242:245], v78, s[6:7] offset:448
	global_load_dwordx4 v[246:249], v78, s[6:7] offset:480
	s_add_i32 s22, s22, s34
	s_add_i32 s4, s4, s5
	s_add_i32 s14, s14, s15
	s_add_i32 s16, s16, s17
	s_cmpk_gt_i32 s22, 0xff
	s_waitcnt vmcnt(60)
	v_and_b32_e32 v81, 0xffff0000, v42
	s_waitcnt vmcnt(59)
	v_lshlrev_b32_e32 v84, 16, v43
	v_and_b32_e32 v85, 0xffff0000, v43
	s_waitcnt vmcnt(58)
	v_lshlrev_b32_e32 v88, 16, v44
	v_and_b32_e32 v89, 0xffff0000, v44
	s_waitcnt vmcnt(57)
	v_lshlrev_b32_e32 v92, 16, v45
	v_and_b32_e32 v93, 0xffff0000, v45
	s_waitcnt vmcnt(52)
; __device__ __forceinline__ void sb_attn_merge(Frame& F, int u) {
;     ...
;         for (int i = 0; i < 16; i += 2) { const unsigned w0 = ((const unsigned*)P0)[(8 * d + (i >> 1)) * 64], w1 = ((const unsigned*)P1)[(8 * d + (i >> 1)) * 64];
;             oacc[d][i] = bf_lo(w0) + R0 * bf_lo(w1); oacc[d][i + 1] = bf_hi(w0) + R0 * bf_hi(w1); }
	v_lshlrev_b32_e32 v82, 16, v52
	v_and_b32_e32 v83, 0xffff0000, v52
	v_lshlrev_b32_e32 v46, 16, v16
	v_lshlrev_b32_e32 v48, 16, v20
	v_and_b32_e32 v49, 0xffff0000, v20
	v_lshlrev_b32_e32 v56, 16, v21
	v_and_b32_e32 v57, 0xffff0000, v21
	v_lshlrev_b32_e32 v54, 16, v22
	v_and_b32_e32 v55, 0xffff0000, v22
	v_lshlrev_b32_e32 v60, 16, v23
	v_and_b32_e32 v61, 0xffff0000, v23
	v_lshlrev_b32_e32 v58, 16, v24
	v_and_b32_e32 v59, 0xffff0000, v24
	v_lshlrev_b32_e32 v62, 16, v25
	v_and_b32_e32 v63, 0xffff0000, v25
	v_lshlrev_b32_e32 v20, 16, v26
	v_and_b32_e32 v21, 0xffff0000, v26
	v_lshlrev_b32_e32 v66, 16, v27
	v_and_b32_e32 v67, 0xffff0000, v27
	v_lshlrev_b32_e32 v64, 16, v28
	v_and_b32_e32 v65, 0xffff0000, v28
	v_lshlrev_b32_e32 v70, 16, v29
	v_and_b32_e32 v71, 0xffff0000, v29
	v_lshlrev_b32_e32 v68, 16, v30
	v_and_b32_e32 v69, 0xffff0000, v30
	v_lshlrev_b32_e32 v74, 16, v31
	v_and_b32_e32 v75, 0xffff0000, v31
	v_lshlrev_b32_e32 v72, 16, v32
	v_and_b32_e32 v73, 0xffff0000, v32
	v_lshlrev_b32_e32 v76, 16, v33
	v_and_b32_e32 v77, 0xffff0000, v33
	s_waitcnt vmcnt(48)
	v_lshlrev_b32_e32 v22, 16, v80
	v_and_b32_e32 v23, 0xffff0000, v80
	v_lshlrev_b32_e32 v24, 16, v34
	v_lshlrev_b32_e32 v26, 16, v36
	v_and_b32_e32 v25, 0xffff0000, v34
	v_and_b32_e32 v27, 0xffff0000, v36
	v_lshlrev_b32_e32 v28, 16, v35
	v_lshlrev_b32_e32 v30, 16, v38
	v_and_b32_e32 v29, 0xffff0000, v35
	v_and_b32_e32 v31, 0xffff0000, v38
	v_lshlrev_b32_e32 v32, 16, v37
	v_lshlrev_b32_e32 v36, 16, v40
	v_and_b32_e32 v33, 0xffff0000, v37
	v_and_b32_e32 v37, 0xffff0000, v40
	v_lshlrev_b32_e32 v38, 16, v39
	v_lshlrev_b32_e32 v40, 16, v41
	v_and_b32_e32 v39, 0xffff0000, v39
	v_and_b32_e32 v41, 0xffff0000, v41
	v_lshlrev_b32_e32 v80, 16, v42
	s_waitcnt vmcnt(35)
	v_lshlrev_b32_e32 v13, 16, v118
	v_lshlrev_b32_e32 v15, 16, v116
	v_and_b32_e32 v12, 0xffff0000, v118
	v_and_b32_e32 v14, 0xffff0000, v116
	s_waitcnt vmcnt(34)
	v_lshlrev_b32_e32 v35, 16, v119
	v_lshlrev_b32_e32 v43, 16, v117
	v_and_b32_e32 v34, 0xffff0000, v119
	v_and_b32_e32 v42, 0xffff0000, v117
	v_and_b32_e32 v47, 0xffff0000, v16
	v_lshlrev_b32_e32 v50, 16, v17
	v_and_b32_e32 v51, 0xffff0000, v17
	s_waitcnt vmcnt(31)
	v_pk_fma_f32 v[16:17], v[18:19], v[14:15], v[12:13] op_sel_hi:[0,1,1]
	v_pk_fma_f32 v[12:13], v[18:19], v[42:43], v[34:35] op_sel_hi:[0,1,1]
	v_pk_fma_f32 v[34:35], v[18:19], v[30:31], v[28:29] op_sel_hi:[0,1,1]
	v_pk_fma_f32 v[30:31], v[18:19], v[40:41], v[38:39] op_sel_hi:[0,1,1]
	v_pk_fma_f32 v[40:41], v[18:19], v[82:83], v[80:81] op_sel_hi:[0,1,1]
	s_waitcnt vmcnt(30)
	v_lshlrev_b32_e32 v80, 16, v122
	v_and_b32_e32 v81, 0xffff0000, v122
	v_lshlrev_b32_e32 v86, 16, v53
	v_and_b32_e32 v87, 0xffff0000, v53
	v_lshlrev_b32_e32 v90, 16, v91
	v_and_b32_e32 v91, 0xffff0000, v91
	v_lshlrev_b32_e32 v94, 16, v95
	v_and_b32_e32 v95, 0xffff0000, v95
	v_lshlrev_b32_e32 v96, 16, v97
	v_lshlrev_b32_e32 v98, 16, v99
	v_and_b32_e32 v97, 0xffff0000, v97
	v_and_b32_e32 v99, 0xffff0000, v99
	v_lshlrev_b32_e32 v100, 16, v101
	v_lshlrev_b32_e32 v102, 16, v103
	v_and_b32_e32 v101, 0xffff0000, v101
	v_and_b32_e32 v103, 0xffff0000, v103
	v_lshlrev_b32_e32 v104, 16, v105
	v_lshlrev_b32_e32 v106, 16, v107
	v_and_b32_e32 v105, 0xffff0000, v105
	v_and_b32_e32 v107, 0xffff0000, v107
	v_lshlrev_b32_e32 v108, 16, v109
	v_lshlrev_b32_e32 v110, 16, v111
	v_and_b32_e32 v109, 0xffff0000, v109
	v_and_b32_e32 v111, 0xffff0000, v111
	v_lshlrev_b32_e32 v45, 16, v120
	v_lshlrev_b32_e32 v53, 16, v121
	v_and_b32_e32 v44, 0xffff0000, v120
	v_and_b32_e32 v52, 0xffff0000, v121
	s_waitcnt vmcnt(29)
	v_lshlrev_b32_e32 v82, 16, v123
	v_and_b32_e32 v83, 0xffff0000, v123
	v_pk_fma_f32 v[46:47], v[18:19], v[80:81], v[46:47] op_sel_hi:[0,1,1]
	v_lshlrev_b32_e32 v112, 16, v113
	v_lshlrev_b32_e32 v114, 16, v115
	v_and_b32_e32 v113, 0xffff0000, v113
	v_and_b32_e32 v115, 0xffff0000, v115
	v_pk_fma_f32 v[14:15], v[18:19], v[52:53], v[44:45] op_sel_hi:[0,1,1]
	v_pk_fma_f32 v[52:53], v[18:19], v[22:23], v[20:21] op_sel_hi:[0,1,1]
	v_pk_fma_f32 v[44:45], v[18:19], v[26:27], v[24:25] op_sel_hi:[0,1,1]
	v_pk_fma_f32 v[42:43], v[18:19], v[36:37], v[32:33] op_sel_hi:[0,1,1]
	v_pk_fma_f32 v[28:29], v[18:19], v[86:87], v[84:85] op_sel_hi:[0,1,1]
	v_pk_fma_f32 v[26:27], v[18:19], v[94:95], v[92:93] op_sel_hi:[0,1,1]
	v_pk_fma_f32 v[38:39], v[18:19], v[90:91], v[88:89] op_sel_hi:[0,1,1]
	v_pk_fma_f32 v[24:25], v[18:19], v[102:103], v[100:101] op_sel_hi:[0,1,1]
	v_pk_fma_f32 v[36:37], v[18:19], v[98:99], v[96:97] op_sel_hi:[0,1,1]
	v_pk_fma_f32 v[20:21], v[18:19], v[110:111], v[108:109] op_sel_hi:[0,1,1]
	v_pk_fma_f32 v[32:33], v[18:19], v[106:107], v[104:105] op_sel_hi:[0,1,1]
	s_waitcnt vmcnt(28)
	v_lshlrev_b32_e32 v84, 16, v124
	v_and_b32_e32 v85, 0xffff0000, v124
	s_waitcnt vmcnt(27)
	v_lshlrev_b32_e32 v86, 16, v125
	v_and_b32_e32 v87, 0xffff0000, v125
	s_waitcnt vmcnt(26)
	v_lshlrev_b32_e32 v88, 16, v126
	v_and_b32_e32 v89, 0xffff0000, v126
	s_waitcnt vmcnt(25)
	v_lshlrev_b32_e32 v90, 16, v127
	v_and_b32_e32 v91, 0xffff0000, v127
	s_waitcnt vmcnt(24)
	v_lshlrev_b32_e32 v92, 16, v128
	v_and_b32_e32 v93, 0xffff0000, v128
	s_waitcnt vmcnt(23)
	v_lshlrev_b32_e32 v94, 16, v129
	v_and_b32_e32 v95, 0xffff0000, v129
	s_waitcnt vmcnt(22)
	v_lshlrev_b32_e32 v96, 16, v130
	v_and_b32_e32 v97, 0xffff0000, v130
	s_waitcnt vmcnt(21)
	v_lshlrev_b32_e32 v98, 16, v131
	v_and_b32_e32 v99, 0xffff0000, v131
	s_waitcnt vmcnt(20)
	v_lshlrev_b32_e32 v100, 16, v132
	v_and_b32_e32 v101, 0xffff0000, v132
	s_waitcnt vmcnt(19)
	v_lshlrev_b32_e32 v102, 16, v133
	v_and_b32_e32 v103, 0xffff0000, v133
	s_waitcnt vmcnt(18)
	v_lshlrev_b32_e32 v104, 16, v134
	v_and_b32_e32 v105, 0xffff0000, v134
	s_waitcnt vmcnt(17)
; __device__ __forceinline__ void sb_attn_merge(Frame& F, int u) {
;     ...
;     float ss = 0.f;
; #pragma unroll
;     for (int d = 0; d < 4; ++d)
; #pragma unroll
;         for (int i = 0; i < 16; ++i) ss += oacc[d][i] * oacc[d][i];
;     ss += __shfl_xor(ss, 32);
;     const float rs = rsqrtf(ss * (1.f / HD) + EPS);
	v_lshlrev_b32_e32 v106, 16, v135
	v_and_b32_e32 v107, 0xffff0000, v135
	s_waitcnt vmcnt(16)
	v_lshlrev_b32_e32 v108, 16, v136
	v_and_b32_e32 v109, 0xffff0000, v136
	v_pk_fma_f32 v[50:51], v[18:19], v[82:83], v[50:51] op_sel_hi:[0,1,1]
	v_pk_mul_f32 v[82:83], v[46:47], v[46:47]
	v_pk_fma_f32 v[22:23], v[18:19], v[114:115], v[112:113] op_sel_hi:[0,1,1]
	v_pk_fma_f32 v[56:57], v[18:19], v[86:87], v[56:57] op_sel_hi:[0,1,1]
	v_pk_fma_f32 v[48:49], v[18:19], v[84:85], v[48:49] op_sel_hi:[0,1,1]
	v_pk_fma_f32 v[60:61], v[18:19], v[90:91], v[60:61] op_sel_hi:[0,1,1]
	v_pk_fma_f32 v[54:55], v[18:19], v[88:89], v[54:55] op_sel_hi:[0,1,1]
	v_pk_fma_f32 v[62:63], v[18:19], v[94:95], v[62:63] op_sel_hi:[0,1,1]
	v_pk_fma_f32 v[58:59], v[18:19], v[92:93], v[58:59] op_sel_hi:[0,1,1]
	v_pk_fma_f32 v[66:67], v[18:19], v[96:97], v[66:67] op_sel_hi:[0,1,1]
	v_pk_fma_f32 v[70:71], v[18:19], v[100:101], v[70:71] op_sel_hi:[0,1,1]
	v_pk_fma_f32 v[64:65], v[18:19], v[98:99], v[64:65] op_sel_hi:[0,1,1]
	v_pk_fma_f32 v[74:75], v[18:19], v[104:105], v[74:75] op_sel_hi:[0,1,1]
	v_pk_fma_f32 v[68:69], v[18:19], v[102:103], v[68:69] op_sel_hi:[0,1,1]
	v_pk_fma_f32 v[76:77], v[18:19], v[108:109], v[76:77] op_sel_hi:[0,1,1]
	v_pk_fma_f32 v[72:73], v[18:19], v[106:107], v[72:73] op_sel_hi:[0,1,1]
	v_pk_mul_f32 v[80:81], v[50:51], v[50:51]
	v_add_f32_e32 v18, v82, v83
	v_add_f32_e32 v18, v18, v80
	v_pk_mul_f32 v[86:87], v[48:49], v[48:49]
	v_add_f32_e32 v18, v81, v18
	v_add_f32_e32 v18, v18, v86
	v_pk_mul_f32 v[84:85], v[56:57], v[56:57]
	v_add_f32_e32 v18, v87, v18
	v_add_f32_e32 v18, v18, v84
	v_pk_mul_f32 v[90:91], v[54:55], v[54:55]
	v_add_f32_e32 v18, v85, v18
	v_add_f32_e32 v18, v18, v90
	v_pk_mul_f32 v[88:89], v[60:61], v[60:61]
	v_add_f32_e32 v18, v91, v18
	v_add_f32_e32 v18, v18, v88
	v_pk_mul_f32 v[94:95], v[58:59], v[58:59]
	v_add_f32_e32 v18, v89, v18
	v_add_f32_e32 v18, v18, v94
	v_pk_mul_f32 v[92:93], v[62:63], v[62:63]
	v_add_f32_e32 v18, v95, v18
	v_add_f32_e32 v18, v18, v92
	v_pk_mul_f32 v[116:117], v[52:53], v[52:53]
	v_add_f32_e32 v18, v93, v18
	v_add_f32_e32 v18, v18, v116
	v_pk_mul_f32 v[96:97], v[66:67], v[66:67]
	v_add_f32_e32 v18, v117, v18
	v_add_f32_e32 v18, v18, v96
	v_pk_mul_f32 v[100:101], v[64:65], v[64:65]
	v_add_f32_e32 v18, v97, v18
	v_add_f32_e32 v18, v18, v100
	v_pk_mul_f32 v[98:99], v[70:71], v[70:71]
	v_add_f32_e32 v18, v101, v18
	v_add_f32_e32 v18, v18, v98
	v_pk_mul_f32 v[104:105], v[68:69], v[68:69]
	v_add_f32_e32 v18, v99, v18
	v_add_f32_e32 v18, v18, v104
	v_pk_mul_f32 v[102:103], v[74:75], v[74:75]
	v_add_f32_e32 v18, v105, v18
	v_add_f32_e32 v18, v18, v102
	v_pk_mul_f32 v[108:109], v[72:73], v[72:73]
	v_add_f32_e32 v18, v103, v18
	v_add_f32_e32 v18, v18, v108
	v_pk_mul_f32 v[106:107], v[76:77], v[76:77]
	v_add_f32_e32 v18, v109, v18
	v_add_f32_e32 v18, v18, v106
	v_pk_mul_f32 v[120:121], v[44:45], v[44:45]
	v_add_f32_e32 v18, v107, v18
	v_add_f32_e32 v18, v18, v120
	v_pk_mul_f32 v[118:119], v[34:35], v[34:35]
	v_add_f32_e32 v18, v121, v18
	v_add_f32_e32 v18, v18, v118
	v_pk_mul_f32 v[124:125], v[42:43], v[42:43]
	v_add_f32_e32 v18, v119, v18
	v_add_f32_e32 v18, v18, v124
	v_pk_mul_f32 v[122:123], v[30:31], v[30:31]
	v_add_f32_e32 v18, v125, v18
	v_add_f32_e32 v18, v18, v122
	v_pk_mul_f32 v[128:129], v[40:41], v[40:41]
	v_add_f32_e32 v18, v123, v18
	v_add_f32_e32 v18, v18, v128
	v_pk_mul_f32 v[126:127], v[28:29], v[28:29]
	v_add_f32_e32 v18, v129, v18
	v_add_f32_e32 v18, v18, v126
	v_pk_mul_f32 v[132:133], v[38:39], v[38:39]
	v_add_f32_e32 v18, v127, v18
	v_add_f32_e32 v18, v18, v132
	v_pk_mul_f32 v[130:131], v[26:27], v[26:27]
	v_add_f32_e32 v18, v133, v18
	v_add_f32_e32 v18, v18, v130
	v_pk_mul_f32 v[136:137], v[36:37], v[36:37]
	v_add_f32_e32 v18, v131, v18
	v_add_f32_e32 v18, v18, v136
	v_pk_mul_f32 v[134:135], v[24:25], v[24:25]
	v_add_f32_e32 v18, v137, v18
	v_add_f32_e32 v18, v18, v134
	v_pk_mul_f32 v[140:141], v[32:33], v[32:33]
	v_add_f32_e32 v18, v135, v18
	v_add_f32_e32 v18, v18, v140
	v_pk_mul_f32 v[138:139], v[20:21], v[20:21]
	v_add_f32_e32 v18, v141, v18
	v_add_f32_e32 v18, v18, v138
	v_pk_mul_f32 v[142:143], v[22:23], v[22:23]
	v_add_f32_e32 v18, v139, v18
	v_add_f32_e32 v18, v18, v142
	v_pk_mul_f32 v[110:111], v[16:17], v[16:17]
	v_add_f32_e32 v18, v143, v18
	v_add_f32_e32 v18, v18, v111
	v_pk_mul_f32 v[112:113], v[12:13], v[12:13]
	v_add_f32_e32 v18, v110, v18
	v_add_f32_e32 v18, v18, v113
	v_pk_mul_f32 v[114:115], v[14:15], v[14:15]
	v_add_f32_e32 v18, v112, v18
	v_add_f32_e32 v18, v18, v115
	v_add_f32_e32 v18, v114, v18
	ds_bpermute_b32 v80, v1, v18
	s_waitcnt lgkmcnt(0)
	v_add_f32_e32 v18, v18, v80
	v_fmamk_f32 v18, v18, 0x3c000000, v79
	v_mul_f32_e32 v80, 0x4b800000, v18
	v_cmp_gt_f32_e32 vcc, s21, v18
	s_nop 1
	v_cndmask_b32_e32 v18, v18, v80, vcc
	v_rsq_f32_e32 v18, v18
	s_nop 0
	v_mul_f32_e32 v80, 0x45800000, v18
	v_cndmask_b32_e32 v18, v18, v80, vcc
	v_pk_mul_f32 v[46:47], v[46:47], v[18:19] op_sel_hi:[1,0]
	v_pk_mul_f32 v[50:51], v[50:51], v[18:19] op_sel_hi:[1,0]
	s_waitcnt vmcnt(0)
; __device__ __forceinline__ unsigned cvt2bf(float lo, float hi) { const f32x2 v = {lo, hi}; return __builtin_bit_cast(unsigned, __builtin_convertvector(v, bf16x2_t)); }
; __device__ __forceinline__ void sb_attn_merge(Frame& F, int u) {
;     ...
; #pragma unroll
;     for (int d = 0; d < 4; ++d)
; #pragma unroll
;         for (int g = 0; g < 4; ++g) { const int dd = 32 * d + 8 * g + 4 * hh; const f32x4 w4 = *(const f32x4*)(nw + dd);
;             v2u w; w.x = cvt2bf(oacc[d][4 * g] * rs * w4.x, oacc[d][4 * g + 1] * rs * w4.y); w.y = cvt2bf(oacc[d][4 * g + 2] * rs * w4.z, oacc[d][4 * g + 3] * rs * w4.w);
;             *(v2u*)(op + 32 * d + 8 * g) = w; }
	v_pk_mul_f32 v[2:3], v[2:3], v[46:47]
	v_pk_mul_f32 v[4:5], v[4:5], v[50:51]
	v_cvt_pk_bf16_f32 v2, v2, v3
	v_cvt_pk_bf16_f32 v3, v4, v5
	global_store_dwordx2 v[10:11], v[2:3], off
	v_mov_b32_e32 v2, v184
	v_mov_b32_e32 v3, v185
	v_mov_b32_e32 v4, v186
	v_mov_b32_e32 v5, v187
	v_pk_mul_f32 v[46:47], v[48:49], v[18:19] op_sel_hi:[1,0]
	v_pk_mul_f32 v[48:49], v[56:57], v[18:19] op_sel_hi:[1,0]
	v_pk_mul_f32 v[44:45], v[44:45], v[18:19] op_sel_hi:[1,0]
	v_pk_mul_f32 v[34:35], v[34:35], v[18:19] op_sel_hi:[1,0]
	v_pk_mul_f32 v[30:31], v[30:31], v[18:19] op_sel_hi:[1,0]
	v_pk_mul_f32 v[28:29], v[28:29], v[18:19] op_sel_hi:[1,0]
	v_pk_mul_f32 v[26:27], v[26:27], v[18:19] op_sel_hi:[1,0]
	v_pk_mul_f32 v[24:25], v[24:25], v[18:19] op_sel_hi:[1,0]
	v_pk_mul_f32 v[20:21], v[20:21], v[18:19] op_sel_hi:[1,0]
	v_pk_mul_f32 v[16:17], v[16:17], v[18:19] op_sel_hi:[1,0]
	v_pk_mul_f32 v[12:13], v[12:13], v[18:19] op_sel_hi:[1,0]
	v_pk_mul_f32 v[14:15], v[14:15], v[18:19] op_sel_hi:[1,0]
	v_pk_mul_f32 v[2:3], v[2:3], v[46:47]
	v_pk_mul_f32 v[4:5], v[4:5], v[48:49]
	v_cvt_pk_bf16_f32 v2, v2, v3
	v_cvt_pk_bf16_f32 v3, v4, v5
	global_store_dwordx2 v[10:11], v[2:3], off offset:16
	v_mov_b32_e32 v2, v188
	v_mov_b32_e32 v3, v189
	v_mov_b32_e32 v4, v190
	v_mov_b32_e32 v5, v191
	v_pk_mul_f32 v[46:47], v[54:55], v[18:19] op_sel_hi:[1,0]
	v_pk_mul_f32 v[48:49], v[60:61], v[18:19] op_sel_hi:[1,0]
	v_pk_mul_f32 v[2:3], v[2:3], v[46:47]
	v_pk_mul_f32 v[4:5], v[4:5], v[48:49]
	v_cvt_pk_bf16_f32 v2, v2, v3
	v_cvt_pk_bf16_f32 v3, v4, v5
	global_store_dwordx2 v[10:11], v[2:3], off offset:32
	v_mov_b32_e32 v2, v192
	v_mov_b32_e32 v3, v193
	v_mov_b32_e32 v4, v194
	v_mov_b32_e32 v5, v195
	v_pk_mul_f32 v[46:47], v[58:59], v[18:19] op_sel_hi:[1,0]
	v_pk_mul_f32 v[48:49], v[62:63], v[18:19] op_sel_hi:[1,0]
	v_pk_mul_f32 v[2:3], v[2:3], v[46:47]
	v_pk_mul_f32 v[4:5], v[4:5], v[48:49]
	v_cvt_pk_bf16_f32 v2, v2, v3
	v_cvt_pk_bf16_f32 v3, v4, v5
	global_store_dwordx2 v[10:11], v[2:3], off offset:48
	v_mov_b32_e32 v2, v200
	v_mov_b32_e32 v3, v201
	v_mov_b32_e32 v4, v202
	v_mov_b32_e32 v5, v203
	v_pk_mul_f32 v[46:47], v[52:53], v[18:19] op_sel_hi:[1,0]
	v_pk_mul_f32 v[48:49], v[66:67], v[18:19] op_sel_hi:[1,0]
	v_pk_mul_f32 v[2:3], v[2:3], v[46:47]
	v_pk_mul_f32 v[4:5], v[4:5], v[48:49]
	v_cvt_pk_bf16_f32 v2, v2, v3
	v_cvt_pk_bf16_f32 v3, v4, v5
	global_store_dwordx2 v[10:11], v[2:3], off offset:64
	v_mov_b32_e32 v2, v204
	v_mov_b32_e32 v3, v205
	v_mov_b32_e32 v4, v206
	v_mov_b32_e32 v5, v207
	v_pk_mul_f32 v[46:47], v[64:65], v[18:19] op_sel_hi:[1,0]
	v_pk_mul_f32 v[48:49], v[70:71], v[18:19] op_sel_hi:[1,0]
	v_pk_mul_f32 v[2:3], v[2:3], v[46:47]
	v_pk_mul_f32 v[4:5], v[4:5], v[48:49]
	v_cvt_pk_bf16_f32 v2, v2, v3
	v_cvt_pk_bf16_f32 v3, v4, v5
	global_store_dwordx2 v[10:11], v[2:3], off offset:80
	v_mov_b32_e32 v2, v208
	v_mov_b32_e32 v3, v209
	v_mov_b32_e32 v4, v210
	v_mov_b32_e32 v5, v211
	v_pk_mul_f32 v[46:47], v[68:69], v[18:19] op_sel_hi:[1,0]
	v_pk_mul_f32 v[48:49], v[74:75], v[18:19] op_sel_hi:[1,0]
	v_pk_mul_f32 v[2:3], v[46:47], v[2:3]
	v_pk_mul_f32 v[4:5], v[48:49], v[4:5]
	v_cvt_pk_bf16_f32 v2, v2, v3
	v_cvt_pk_bf16_f32 v3, v4, v5
	global_store_dwordx2 v[10:11], v[2:3], off offset:96
	v_mov_b32_e32 v2, v212
	v_mov_b32_e32 v3, v213
	v_mov_b32_e32 v4, v214
	v_mov_b32_e32 v5, v215
	v_pk_mul_f32 v[46:47], v[72:73], v[18:19] op_sel_hi:[1,0]
	v_pk_mul_f32 v[48:49], v[76:77], v[18:19] op_sel_hi:[1,0]
	v_pk_mul_f32 v[2:3], v[46:47], v[2:3]
	v_pk_mul_f32 v[4:5], v[48:49], v[4:5]
	v_cvt_pk_bf16_f32 v2, v2, v3
	v_cvt_pk_bf16_f32 v3, v4, v5
	global_store_dwordx2 v[10:11], v[2:3], off offset:112
	v_mov_b32_e32 v2, v218
	v_mov_b32_e32 v3, v219
	v_mov_b32_e32 v4, v220
	v_mov_b32_e32 v5, v221
	v_pk_mul_f32 v[2:3], v[44:45], v[2:3]
	v_pk_mul_f32 v[4:5], v[34:35], v[4:5]
	v_cvt_pk_bf16_f32 v2, v2, v3
	v_cvt_pk_bf16_f32 v3, v4, v5
	global_store_dwordx2 v[10:11], v[2:3], off offset:128
	v_mov_b32_e32 v2, v222
	v_mov_b32_e32 v3, v223
	v_mov_b32_e32 v4, v224
	v_mov_b32_e32 v5, v225
	v_pk_mul_f32 v[34:35], v[42:43], v[18:19] op_sel_hi:[1,0]
	v_pk_mul_f32 v[4:5], v[30:31], v[4:5]
	v_pk_mul_f32 v[2:3], v[34:35], v[2:3]
	v_pk_mul_f32 v[30:31], v[40:41], v[18:19] op_sel_hi:[1,0]
	v_cvt_pk_bf16_f32 v2, v2, v3
	v_cvt_pk_bf16_f32 v3, v4, v5
	global_store_dwordx2 v[10:11], v[2:3], off offset:144
	v_mov_b32_e32 v2, v226
	v_mov_b32_e32 v3, v227
	v_mov_b32_e32 v4, v228
	v_mov_b32_e32 v5, v229
	v_pk_mul_f32 v[2:3], v[30:31], v[2:3]
	v_pk_mul_f32 v[4:5], v[28:29], v[4:5]
	v_cvt_pk_bf16_f32 v2, v2, v3
	v_cvt_pk_bf16_f32 v3, v4, v5
	global_store_dwordx2 v[10:11], v[2:3], off offset:160
	v_mov_b32_e32 v2, v230
	v_mov_b32_e32 v3, v231
	v_mov_b32_e32 v4, v232
	v_mov_b32_e32 v5, v233
	v_pk_mul_f32 v[28:29], v[38:39], v[18:19] op_sel_hi:[1,0]
	v_pk_mul_f32 v[4:5], v[26:27], v[4:5]
	v_pk_mul_f32 v[2:3], v[28:29], v[2:3]
	v_pk_mul_f32 v[26:27], v[36:37], v[18:19] op_sel_hi:[1,0]
	v_cvt_pk_bf16_f32 v2, v2, v3
	v_cvt_pk_bf16_f32 v3, v4, v5
	global_store_dwordx2 v[10:11], v[2:3], off offset:176
	v_mov_b32_e32 v2, v234
	v_mov_b32_e32 v3, v235
	v_mov_b32_e32 v4, v236
	v_mov_b32_e32 v5, v237
	v_pk_mul_f32 v[2:3], v[26:27], v[2:3]
	v_pk_mul_f32 v[4:5], v[24:25], v[4:5]
	v_cvt_pk_bf16_f32 v2, v2, v3
	v_cvt_pk_bf16_f32 v3, v4, v5
	global_store_dwordx2 v[10:11], v[2:3], off offset:192
	v_mov_b32_e32 v2, v238
	v_mov_b32_e32 v3, v239
	v_mov_b32_e32 v4, v240
	v_mov_b32_e32 v5, v241
	v_pk_mul_f32 v[24:25], v[32:33], v[18:19] op_sel_hi:[1,0]
	v_pk_mul_f32 v[4:5], v[20:21], v[4:5]
	v_pk_mul_f32 v[2:3], v[24:25], v[2:3]
	v_pk_mul_f32 v[20:21], v[22:23], v[18:19] op_sel_hi:[1,0]
	v_cvt_pk_bf16_f32 v2, v2, v3
	v_cvt_pk_bf16_f32 v3, v4, v5
	global_store_dwordx2 v[10:11], v[2:3], off offset:208
	v_mov_b32_e32 v2, v242
	v_mov_b32_e32 v3, v243
	v_mov_b32_e32 v4, v244
	v_mov_b32_e32 v5, v245
	v_pk_mul_f32 v[2:3], v[20:21], v[2:3]
	v_pk_mul_f32 v[4:5], v[16:17], v[4:5] op_sel:[1,0] op_sel_hi:[0,1]
	v_cvt_pk_bf16_f32 v2, v2, v3
	v_cvt_pk_bf16_f32 v3, v4, v5
	global_store_dwordx2 v[10:11], v[2:3], off offset:224
	v_mov_b32_e32 v2, v246
	v_mov_b32_e32 v3, v247
	v_mov_b32_e32 v4, v248
	v_mov_b32_e32 v5, v249
	v_pk_mul_f32 v[2:3], v[12:13], v[2:3] op_sel:[1,0] op_sel_hi:[0,1]
	v_pk_mul_f32 v[4:5], v[14:15], v[4:5] op_sel:[1,0] op_sel_hi:[0,1]
	v_cvt_pk_bf16_f32 v2, v2, v3
	v_cvt_pk_bf16_f32 v3, v4, v5
	global_store_dwordx2 v[10:11], v[2:3], off offset:240
	s_cbranch_scc0 .LBB0_1517
